# attention KV loops: packed f32 adds of the softmax split into scalar VALU ops
# speedup vs baseline: 1.0061x; 1.0019x over previous
; DI unsigned pack2(float lo, float hi) { const f32x2 v = (f32x2){lo, hi}; return __builtin_bit_cast(unsigned, __builtin_convertvector(v, bf16x2_t)); }
; #define MFMA32(a, b, c) __builtin_amdgcn_mfma_f32_32x32x16_bf16((a), (b), (c), 0, 0, 0)
; template <int DQK, int MODE>
; DI void attn_phase(const bf16_t* __restrict__ QK, int ldq, const bf16_t* __restrict__ Vt, int VC, bf16_t* __restrict__ O, int ldo, int nhu, bool skip_ctx, const float* __restrict__ qgain, const f32x2* __restrict__ rope, float qscale, char* shm) {
;     ...
;             { const f32x2 m2 = (f32x2){mrun, mrun}; f32x2 ps2 = (f32x2){0.f, 0.f};
; #pragma unroll
;               for (int i = 0; i < 16; i += 2) {
;                   f32x2 a = (f32x2){st0[i], st0[i + 1]} - m2, c = (f32x2){st1[i], st1[i + 1]} - m2;
;                   a[0] = __builtin_amdgcn_exp2f(a[0]); a[1] = __builtin_amdgcn_exp2f(a[1]); c[0] = __builtin_amdgcn_exp2f(c[0]); c[1] = __builtin_amdgcn_exp2f(c[1]);
;                   ps2 += a; ps2 += c; st0[i] = a[0]; st0[i + 1] = a[1]; st1[i] = c[0]; st1[i + 1] = c[1]; }
;               lsum += ps2[0] + ps2[1]; }
; #pragma unroll
;             for (int kb = 0; kb < 2; ++kb)
; #pragma unroll
;                 for (int s = 0; s < 2; ++s) {
;                     u32x4 pw;
;                     if (kb == 0) { pw.x = pack2(st0[8 * s], st0[8 * s + 1]); pw.y = pack2(st0[8 * s + 2], st0[8 * s + 3]); pw.z = pack2(st0[8 * s + 4], st0[8 * s + 5]); pw.w = pack2(st0[8 * s + 6], st0[8 * s + 7]); }
;                     else { pw.x = pack2(st1[8 * s], st1[8 * s + 1]); pw.y = pack2(st1[8 * s + 2], st1[8 * s + 3]); pw.z = pack2(st1[8 * s + 4], st1[8 * s + 5]); pw.w = pack2(st1[8 * s + 6], st1[8 * s + 7]); }
;                     const bf16x8 pb = __builtin_bit_cast(bf16x8, pw);
; #pragma unroll
;                     for (int t = 0; t < 4; ++t) {
;                         const bf16x8 a = *(const bf16x8*)(Vc + (32 * t + r) * VS + (kb * 2 + s) * 32 + h * 16);
;                         oacc[t] = MFMA32(a, pb, oacc[t]);
;                     }
;                 }
.LBB0_1287:
	v_mov_b32_e32 v97, v156
	v_pk_add_f32 v[80:81], v[80:81], v[96:97] neg_lo:[0,1] neg_hi:[0,1]
	v_pk_add_f32 v[88:89], v[88:89], v[96:97] neg_lo:[0,1] neg_hi:[0,1]
	v_exp_f32_e32 v114, v80
	v_exp_f32_e32 v115, v81
	v_pk_add_f32 v[80:81], v[82:83], v[96:97] neg_lo:[0,1] neg_hi:[0,1]
	ds_read_b128 v[98:101], v163 offset:36896
	v_exp_f32_e32 v116, v80
	v_exp_f32_e32 v117, v81
	v_pk_add_f32 v[80:81], v[84:85], v[96:97] neg_lo:[0,1] neg_hi:[0,1]
	v_pk_add_f32 v[84:85], v[86:87], v[96:97] neg_lo:[0,1] neg_hi:[0,1]
	v_exp_f32_e32 v118, v80
	v_exp_f32_e32 v119, v81
	ds_read_b128 v[80:83], v163 offset:36864
	v_exp_f32_e32 v120, v84
	v_exp_f32_e32 v121, v85
	v_cvt_pk_bf16_f32 v84, v114, v115
	v_cvt_pk_bf16_f32 v85, v116, v117
	v_cvt_pk_bf16_f32 v86, v118, v119
	v_cvt_pk_bf16_f32 v87, v120, v121
	v_exp_f32_e32 v122, v88
	v_exp_f32_e32 v123, v89
	s_waitcnt lgkmcnt(0)
	v_mfma_f32_32x32x16_bf16 v[48:63], v[80:83], v[84:87], v[48:63]
	ds_read_b128 v[80:83], v163 offset:41472
	ds_read_b128 v[102:105], v163 offset:41504
	v_add_f32_e64 v64, v64, -v96
	v_add_f32_e64 v65, v65, -v97
	v_add_f32_e64 v72, v72, -v96
	v_add_f32_e64 v73, v73, -v97
	v_exp_f32_e32 v88, v64
	v_exp_f32_e32 v89, v65
	v_pk_add_f32 v[64:65], v[66:67], v[96:97] neg_lo:[0,1] neg_hi:[0,1]
	v_exp_f32_e32 v72, v72
	s_waitcnt lgkmcnt(1)
	v_mfma_f32_32x32x16_bf16 v[32:47], v[80:83], v[84:87], v[32:47]
	ds_read_b128 v[80:83], v163 offset:46080
	ds_read_b128 v[106:109], v163 offset:50688
	ds_read_b128 v[110:113], v163 offset:46112
	v_exp_f32_e32 v73, v73
	s_lshl_b32 s0, s31, 7
	s_ashr_i32 s1, s0, 31
	s_add_i32 s7, s7, s26
	s_cmpk_gt_i32 s7, 0x47f
	s_waitcnt lgkmcnt(2)
	v_mfma_f32_32x32x16_bf16 v[16:31], v[80:83], v[84:87], v[16:31]
	v_add_f32_e64 v80, v90, -v96
	v_add_f32_e64 v81, v91, -v97
	v_add_f32_e64 v90, v114, 0
	v_add_f32_e64 v91, v115, 0
	v_exp_f32_e32 v150, v80
	v_exp_f32_e32 v151, v81
	v_pk_add_f32 v[80:81], v[92:93], v[96:97] neg_lo:[0,1] neg_hi:[0,1]
	v_exp_f32_e32 v92, v64
	v_exp_f32_e32 v152, v80
	s_waitcnt lgkmcnt(1)
	v_mfma_f32_32x32x16_bf16 v[0:15], v[106:109], v[84:87], v[0:15]
	v_add_f32_e64 v84, v94, -v96
	v_add_f32_e64 v85, v95, -v97
	v_exp_f32_e32 v153, v81
	v_exp_f32_e32 v106, v84
	v_exp_f32_e32 v107, v85
	v_exp_f32_e32 v93, v65
	v_pk_add_f32 v[64:65], v[68:69], v[96:97] neg_lo:[0,1] neg_hi:[0,1]
	ds_read_b128 v[80:83], v163 offset:50720
	v_cvt_pk_bf16_f32 v84, v122, v123
	v_cvt_pk_bf16_f32 v85, v150, v151
	v_cvt_pk_bf16_f32 v86, v152, v153
	v_cvt_pk_bf16_f32 v87, v106, v107
	v_exp_f32_e32 v94, v64
	v_exp_f32_e32 v95, v65
	ds_read_b128 v[64:67], v163 offset:36928
	v_mfma_f32_32x32x16_bf16 v[48:63], v[98:101], v[84:87], v[48:63]
	v_add_f32_e64 v68, v70, -v96
	v_add_f32_e64 v69, v71, -v97
	v_cvt_pk_bf16_f32 v70, v94, v95
	v_exp_f32_e32 v98, v68
	v_exp_f32_e32 v99, v69
	v_cvt_pk_bf16_f32 v68, v88, v89
	v_cvt_pk_bf16_f32 v69, v92, v93
	v_cvt_pk_bf16_f32 v71, v98, v99
	v_mfma_f32_32x32x16_bf16 v[32:47], v[102:105], v[84:87], v[32:47]
	s_waitcnt lgkmcnt(2)
	v_mfma_f32_32x32x16_bf16 v[16:31], v[110:113], v[84:87], v[16:31]
	s_waitcnt lgkmcnt(0)
	v_mfma_f32_32x32x16_bf16 v[48:63], v[64:67], v[68:71], v[48:63]
	v_add_f32_e64 v64, v88, v90
	v_add_f32_e64 v65, v89, v91
	v_add_f32_e64 v64, v116, v64
	v_add_f32_e64 v65, v117, v65
	v_add_f32_e64 v64, v92, v64
	v_add_f32_e64 v65, v93, v65
	v_add_f32_e32 v64, v118, v64
	v_add_f32_e32 v65, v119, v65
	v_mfma_f32_32x32x16_bf16 v[0:15], v[80:83], v[84:87], v[0:15]
	ds_read_b128 v[80:83], v163 offset:41536
	ds_read_b128 v[84:87], v163 offset:36960
	v_add_f32_e64 v92, v94, v64
	v_add_f32_e64 v93, v95, v65
	ds_read_b128 v[64:67], v163 offset:46144
	ds_read_b128 v[88:91], v163 offset:41568
	s_waitcnt lgkmcnt(3)
	v_mfma_f32_32x32x16_bf16 v[32:47], v[80:83], v[68:71], v[32:47]
	v_add_f32_e64 v80, v120, v92
	v_add_f32_e64 v81, v121, v93
	v_add_f32_e64 v98, v98, v80
	v_add_f32_e64 v99, v99, v81
	ds_read_b128 v[80:83], v163 offset:50752
	ds_read_b128 v[92:95], v163 offset:46176
	s_waitcnt lgkmcnt(3)
	v_mfma_f32_32x32x16_bf16 v[16:31], v[64:67], v[68:71], v[16:31]
	v_add_f32_e64 v64, v74, -v96
	v_add_f32_e64 v65, v75, -v97
	v_exp_f32_e32 v74, v64
	v_exp_f32_e32 v75, v65
	v_pk_add_f32 v[64:65], v[76:77], v[96:97] neg_lo:[0,1] neg_hi:[0,1]
	s_nop 0
	v_exp_f32_e32 v76, v64
	s_waitcnt lgkmcnt(1)
	v_mfma_f32_32x32x16_bf16 v[0:15], v[80:83], v[68:71], v[0:15]
	v_add_f32_e64 v68, v78, -v96
	v_add_f32_e64 v69, v79, -v97
	v_add_f32_e64 v80, v122, v98
	v_add_f32_e64 v81, v123, v99
	v_exp_f32_e32 v77, v65
	v_exp_f32_e32 v78, v68
	v_cvt_pk_bf16_f32 v68, v72, v73
	v_add_f32_e32 v72, v72, v80
	v_add_f32_e32 v73, v73, v81
	v_exp_f32_e32 v79, v69
	v_add_f32_e32 v72, v150, v72
	v_add_f32_e32 v73, v151, v73
	ds_read_b128 v[64:67], v163 offset:50784
	v_add_f32_e32 v72, v74, v72
	v_add_f32_e32 v73, v75, v73
	v_cvt_pk_bf16_f32 v69, v74, v75
	v_add_f32_e32 v72, v152, v72
	v_add_f32_e32 v73, v153, v73
	v_cvt_pk_bf16_f32 v70, v76, v77
	v_add_f32_e32 v72, v76, v72
	v_add_f32_e32 v73, v77, v73
	v_cvt_pk_bf16_f32 v71, v78, v79
	v_add_f32_e32 v72, v106, v72
	v_add_f32_e32 v73, v107, v73
	s_waitcnt lgkmcnt(0)
	v_add_f32_e32 v72, v78, v72
	v_add_f32_e32 v73, v79, v73
	v_mfma_f32_32x32x16_bf16 v[48:63], v[84:87], v[68:71], v[48:63]
	v_add_f32_e32 v72, v72, v73
	v_add_f32_e32 v72, v166, v72
	v_mov_b32_e32 v73, v72
	s_nop 1
	v_permlane32_swap_b32_e32 v72, v73
	v_add_f32_e32 v72, v72, v73
	v_div_scale_f32 v73, s[10:11], v72, v72, 1.0
	v_rcp_f32_e32 v74, v73
	v_mfma_f32_32x32x16_bf16 v[32:47], v[88:91], v[68:71], v[32:47]
	s_barrier
; DI unsigned pack2(float lo, float hi) { const f32x2 v = (f32x2){lo, hi}; return __builtin_bit_cast(unsigned, __builtin_convertvector(v, bf16x2_t)); }
; DI float half_swap_sum(float x) { const unsigned u = __float_as_uint(x); const auto r = __builtin_amdgcn_permlane32_swap(u, u, false, false); return __uint_as_float(r[0]) + __uint_as_float(r[1]); }
; template <int DQK, int MODE>
; DI void attn_phase(const bf16_t* __restrict__ QK, int ldq, const bf16_t* __restrict__ Vt, int VC, bf16_t* __restrict__ O, int ldo, int nhu, bool skip_ctx, const float* __restrict__ qgain, const f32x2* __restrict__ rope, float qscale, char* shm) {
;     ...
;         const float l = half_swap_sum(lsum), inv = 1.f / l;
;         bf16_t* op = O + qrow * ldo + ooff;
; #pragma unroll
;         for (int t = 0; t < 4; ++t)
; #pragma unroll
;             for (int g = 0; g < 4; g += 2) {
;                 const unsigned ax = pack2(oacc[t][4 * g] * inv, oacc[t][4 * g + 1] * inv), ay = pack2(oacc[t][4 * g + 2] * inv, oacc[t][4 * g + 3] * inv);
;                 const unsigned bx_ = pack2(oacc[t][4 * g + 4] * inv, oacc[t][4 * g + 5] * inv), by_ = pack2(oacc[t][4 * g + 6] * inv, oacc[t][4 * g + 7] * inv);
;                 const auto sx = __builtin_amdgcn_permlane32_swap(ax, bx_, false, false); const auto sy = __builtin_amdgcn_permlane32_swap(ay, by_, false, false);
;                 *(u32x4*)(op + 32 * t + 8 * (g + h)) = (u32x4){sx[0], sy[0], sx[1], sy[1]}; }
	v_fma_f32 v75, -v73, v74, 1.0
	v_fmac_f32_e32 v74, v75, v74
	v_mfma_f32_32x32x16_bf16 v[16:31], v[92:95], v[68:71], v[16:31]
	v_mfma_f32_32x32x16_bf16 v[0:15], v[64:67], v[68:71], v[0:15]
	v_div_scale_f32 v64, vcc, 1.0, v72, 1.0
	v_mul_f32_e32 v65, v64, v74
	v_fma_f32 v66, -v73, v65, v64
	v_fmac_f32_e32 v65, v66, v74
	v_fma_f32 v64, -v73, v65, v64
	v_div_fmas_f32 v64, v64, v74, v65
	v_div_fixup_f32 v64, v64, v72, 1.0
	v_pk_mul_f32 v[48:49], v[48:49], v[64:65] op_sel_hi:[1,0]
	v_pk_mul_f32 v[50:51], v[50:51], v[64:65] op_sel_hi:[1,0]
	v_pk_mul_f32 v[32:33], v[32:33], v[64:65] op_sel_hi:[1,0]
	v_pk_mul_f32 v[34:35], v[34:35], v[64:65] op_sel_hi:[1,0]
	v_pk_mul_f32 v[16:17], v[16:17], v[64:65] op_sel_hi:[1,0]
	v_pk_mul_f32 v[18:19], v[18:19], v[64:65] op_sel_hi:[1,0]
	v_pk_mul_f32 v[0:1], v[0:1], v[64:65] op_sel_hi:[1,0]
	v_pk_mul_f32 v[2:3], v[2:3], v[64:65] op_sel_hi:[1,0]
	v_lshl_add_u64 v[66:67], s[2:3], 0, v[148:149]
	v_cvt_pk_bf16_f32 v48, v48, v49
	v_cvt_pk_bf16_f32 v49, v50, v51
	v_pk_mul_f32 v[50:51], v[52:53], v[64:65] op_sel_hi:[1,0]
	v_pk_mul_f32 v[52:53], v[54:55], v[64:65] op_sel_hi:[1,0]
	v_cvt_pk_bf16_f32 v32, v32, v33
	v_cvt_pk_bf16_f32 v33, v34, v35
	v_pk_mul_f32 v[34:35], v[36:37], v[64:65] op_sel_hi:[1,0]
	v_pk_mul_f32 v[36:37], v[38:39], v[64:65] op_sel_hi:[1,0]
	v_cvt_pk_bf16_f32 v16, v16, v17
	v_cvt_pk_bf16_f32 v17, v18, v19
	v_pk_mul_f32 v[18:19], v[20:21], v[64:65] op_sel_hi:[1,0]
	v_pk_mul_f32 v[20:21], v[22:23], v[64:65] op_sel_hi:[1,0]
	v_cvt_pk_bf16_f32 v0, v0, v1
	v_cvt_pk_bf16_f32 v1, v2, v3
	v_pk_mul_f32 v[2:3], v[4:5], v[64:65] op_sel_hi:[1,0]
	v_pk_mul_f32 v[4:5], v[6:7], v[64:65] op_sel_hi:[1,0]
	v_lshl_add_u64 v[66:67], s[0:1], 1, v[66:67]
	v_cvt_pk_bf16_f32 v50, v50, v51
	v_cvt_pk_bf16_f32 v51, v52, v53
	v_cvt_pk_bf16_f32 v34, v34, v35
	v_cvt_pk_bf16_f32 v35, v36, v37
	v_cvt_pk_bf16_f32 v18, v18, v19
	v_cvt_pk_bf16_f32 v19, v20, v21
	v_cvt_pk_bf16_f32 v2, v2, v3
	v_cvt_pk_bf16_f32 v3, v4, v5
	v_permlane32_swap_b32_e32 v48, v50
	v_permlane32_swap_b32_e32 v49, v51
	v_lshl_add_u64 v[52:53], v[66:67], 0, v[128:129]
	v_permlane32_swap_b32_e32 v32, v34
	v_permlane32_swap_b32_e32 v33, v35
	v_permlane32_swap_b32_e32 v16, v18
	v_permlane32_swap_b32_e32 v17, v19
	v_permlane32_swap_b32_e32 v0, v2
	v_permlane32_swap_b32_e32 v1, v3
	global_store_dwordx4 v[52:53], v[48:51], off
	global_store_dwordx4 v[52:53], v[32:35], off offset:64
	global_store_dwordx4 v[52:53], v[16:19], off offset:128
	v_pk_mul_f32 v[48:49], v[56:57], v[64:65] op_sel_hi:[1,0]
	v_pk_mul_f32 v[50:51], v[58:59], v[64:65] op_sel_hi:[1,0]
	v_pk_mul_f32 v[32:33], v[40:41], v[64:65] op_sel_hi:[1,0]
	v_pk_mul_f32 v[34:35], v[42:43], v[64:65] op_sel_hi:[1,0]
	v_pk_mul_f32 v[16:17], v[24:25], v[64:65] op_sel_hi:[1,0]
	v_pk_mul_f32 v[18:19], v[26:27], v[64:65] op_sel_hi:[1,0]
	global_store_dwordx4 v[52:53], v[0:3], off offset:192
	v_cvt_pk_bf16_f32 v48, v48, v49
	v_cvt_pk_bf16_f32 v49, v50, v51
	v_pk_mul_f32 v[0:1], v[8:9], v[64:65] op_sel_hi:[1,0]
	v_pk_mul_f32 v[2:3], v[10:11], v[64:65] op_sel_hi:[1,0]
	v_pk_mul_f32 v[50:51], v[60:61], v[64:65] op_sel_hi:[1,0]
	v_pk_mul_f32 v[54:55], v[62:63], v[64:65] op_sel_hi:[1,0]
	v_cvt_pk_bf16_f32 v32, v32, v33
	v_cvt_pk_bf16_f32 v33, v34, v35
	v_pk_mul_f32 v[34:35], v[44:45], v[64:65] op_sel_hi:[1,0]
	v_pk_mul_f32 v[36:37], v[46:47], v[64:65] op_sel_hi:[1,0]
	v_cvt_pk_bf16_f32 v16, v16, v17
	v_cvt_pk_bf16_f32 v17, v18, v19
	v_pk_mul_f32 v[18:19], v[28:29], v[64:65] op_sel_hi:[1,0]
	v_pk_mul_f32 v[20:21], v[30:31], v[64:65] op_sel_hi:[1,0]
	v_cvt_pk_bf16_f32 v0, v0, v1
	v_cvt_pk_bf16_f32 v1, v2, v3
	v_pk_mul_f32 v[2:3], v[12:13], v[64:65] op_sel_hi:[1,0]
	v_pk_mul_f32 v[4:5], v[14:15], v[64:65] op_sel_hi:[1,0]
	v_cvt_pk_bf16_f32 v50, v50, v51
	v_cvt_pk_bf16_f32 v51, v54, v55
	v_cvt_pk_bf16_f32 v34, v34, v35
	v_cvt_pk_bf16_f32 v35, v36, v37
	v_cvt_pk_bf16_f32 v18, v18, v19
	v_cvt_pk_bf16_f32 v19, v20, v21
	v_cvt_pk_bf16_f32 v2, v2, v3
	v_cvt_pk_bf16_f32 v3, v4, v5
	v_permlane32_swap_b32_e32 v48, v50
	v_permlane32_swap_b32_e32 v49, v51
	v_permlane32_swap_b32_e32 v32, v34
	v_permlane32_swap_b32_e32 v33, v35
	v_permlane32_swap_b32_e32 v16, v18
	v_permlane32_swap_b32_e32 v17, v19
	v_permlane32_swap_b32_e32 v0, v2
	v_permlane32_swap_b32_e32 v1, v3
	global_store_dwordx4 v[52:53], v[48:51], off offset:32
	global_store_dwordx4 v[52:53], v[32:35], off offset:96
	global_store_dwordx4 v[52:53], v[16:19], off offset:160
	global_store_dwordx4 v[52:53], v[0:3], off offset:224
	s_cbranch_scc1 .LBB0_1330

; DI unsigned pack2(float lo, float hi) { const f32x2 v = (f32x2){lo, hi}; return __builtin_bit_cast(unsigned, __builtin_convertvector(v, bf16x2_t)); }
; #define MFMA32(a, b, c) __builtin_amdgcn_mfma_f32_32x32x16_bf16((a), (b), (c), 0, 0, 0)
; template <int DQK, int MODE>
; DI void attn_phase(const bf16_t* __restrict__ QK, int ldq, const bf16_t* __restrict__ Vt, int VC, bf16_t* __restrict__ O, int ldo, int nhu, bool skip_ctx, const float* __restrict__ qgain, const f32x2* __restrict__ rope, float qscale, char* shm) {
;     ...
;             { const f32x2 m2 = (f32x2){mrun, mrun}; f32x2 ps2 = (f32x2){0.f, 0.f};
; #pragma unroll
;               for (int i = 0; i < 16; i += 2) {
;                   f32x2 a = (f32x2){st0[i], st0[i + 1]} - m2, c = (f32x2){st1[i], st1[i + 1]} - m2;
;                   a[0] = __builtin_amdgcn_exp2f(a[0]); a[1] = __builtin_amdgcn_exp2f(a[1]); c[0] = __builtin_amdgcn_exp2f(c[0]); c[1] = __builtin_amdgcn_exp2f(c[1]);
;                   ps2 += a; ps2 += c; st0[i] = a[0]; st0[i + 1] = a[1]; st1[i] = c[0]; st1[i + 1] = c[1]; }
;               lsum += ps2[0] + ps2[1]; }
; #pragma unroll
;             for (int kb = 0; kb < 2; ++kb)
; #pragma unroll
;                 for (int s = 0; s < 2; ++s) {
;                     u32x4 pw;
;                     if (kb == 0) { pw.x = pack2(st0[8 * s], st0[8 * s + 1]); pw.y = pack2(st0[8 * s + 2], st0[8 * s + 3]); pw.z = pack2(st0[8 * s + 4], st0[8 * s + 5]); pw.w = pack2(st0[8 * s + 6], st0[8 * s + 7]); }
;                     else { pw.x = pack2(st1[8 * s], st1[8 * s + 1]); pw.y = pack2(st1[8 * s + 2], st1[8 * s + 3]); pw.z = pack2(st1[8 * s + 4], st1[8 * s + 5]); pw.w = pack2(st1[8 * s + 6], st1[8 * s + 7]); }
;                     const bf16x8 pb = __builtin_bit_cast(bf16x8, pw);
; #pragma unroll
;                     for (int t = 0; t < 4; ++t) {
;                         const bf16x8 a = *(const bf16x8*)(Vc + (32 * t + r) * VS + (kb * 2 + s) * 32 + h * 16);
;                         oacc[t] = MFMA32(a, pb, oacc[t]);
;                     }
;                 }
;             if (kt + 1 < nkt) ATT_STORE((kt + 1) & 1);
;             __syncthreads();
.LBB0_1327:
	v_sub_f32_e32 v80, v80, v156
	v_sub_f32_e32 v81, v81, v156
	v_add_u32_e32 v167, s1, v163
	v_exp_f32_e32 v184, v80
	v_exp_f32_e32 v185, v81
	v_sub_f32_e32 v80, v82, v156
	v_sub_f32_e32 v81, v83, v156
	ds_read_b128 v[168:171], v167 offset:9248
	v_exp_f32_e32 v186, v80
	v_exp_f32_e32 v187, v81
	v_sub_f32_e32 v80, v84, v156
	v_sub_f32_e32 v81, v85, v156
	v_sub_f32_e32 v84, v86, v156
	v_sub_f32_e32 v85, v87, v156
	v_exp_f32_e32 v188, v80
	v_exp_f32_e32 v189, v81
	ds_read_b128 v[80:83], v167 offset:9216
	v_exp_f32_e32 v190, v84
	v_exp_f32_e32 v191, v85
	v_cvt_pk_bf16_f32 v84, v184, v185
	v_cvt_pk_bf16_f32 v85, v186, v187
	v_cvt_pk_bf16_f32 v86, v188, v189
	v_cvt_pk_bf16_f32 v87, v190, v191
	v_sub_f32_e32 v88, v88, v156
	v_sub_f32_e32 v89, v89, v156
	v_sub_f32_e32 v64, v64, v156
	v_sub_f32_e32 v65, v65, v156
	s_waitcnt lgkmcnt(0)
	v_mfma_f32_32x32x16_bf16 v[48:63], v[80:83], v[84:87], v[48:63]
	ds_read_b128 v[80:83], v167 offset:13824
	ds_read_b128 v[172:175], v167 offset:13856
	v_exp_f32_e32 v192, v88
	v_exp_f32_e32 v193, v89
	v_exp_f32_e32 v88, v64
	v_exp_f32_e32 v89, v65
	v_add_f32_e32 v64, 0, v184
	v_add_f32_e32 v65, 0, v185
	v_sub_f32_e32 v72, v72, v156
	v_sub_f32_e32 v73, v73, v156
	s_waitcnt lgkmcnt(1)
	v_mfma_f32_32x32x16_bf16 v[32:47], v[80:83], v[84:87], v[32:47]
	ds_read_b128 v[80:83], v167 offset:18432
	ds_read_b128 v[176:179], v167 offset:23040
	ds_read_b128 v[180:183], v167 offset:18464
	v_exp_f32_e32 v72, v72
	v_exp_f32_e32 v73, v73
	s_cmp_eq_u32 s0, 1
	s_cselect_b32 s0, 0x6c00, 0
	s_add_i32 s10, s10, 1
	s_waitcnt lgkmcnt(2)
	v_mfma_f32_32x32x16_bf16 v[16:31], v[80:83], v[84:87], v[16:31]
	v_add_f32_e64 v80, v90, -v156
	v_add_f32_e64 v81, v91, -v156
	v_add_f32_e64 v90, v88, v64
	v_add_f32_e64 v91, v89, v65
	v_exp_f32_e32 v194, v80
	v_exp_f32_e32 v195, v81
	v_sub_f32_e32 v80, v92, v156
	v_sub_f32_e32 v81, v93, v156
	v_sub_f32_e32 v64, v66, v156
	v_sub_f32_e32 v65, v67, v156
	v_exp_f32_e32 v196, v80
	s_waitcnt lgkmcnt(1)
	v_mfma_f32_32x32x16_bf16 v[0:15], v[176:179], v[84:87], v[0:15]
	v_add_f32_e64 v84, v94, -v156
	v_add_f32_e64 v85, v95, -v156
	v_exp_f32_e32 v197, v81
	v_exp_f32_e32 v176, v84
	v_exp_f32_e32 v177, v85
	v_exp_f32_e32 v92, v64
	v_exp_f32_e32 v93, v65
	v_sub_f32_e32 v64, v68, v156
	v_sub_f32_e32 v65, v69, v156
	ds_read_b128 v[80:83], v167 offset:23072
	v_cvt_pk_bf16_f32 v84, v192, v193
	v_cvt_pk_bf16_f32 v85, v194, v195
	v_cvt_pk_bf16_f32 v86, v196, v197
	v_cvt_pk_bf16_f32 v87, v176, v177
	v_exp_f32_e32 v94, v64
	v_exp_f32_e32 v95, v65
	ds_read_b128 v[64:67], v167 offset:9280
	v_mfma_f32_32x32x16_bf16 v[48:63], v[168:171], v[84:87], v[48:63]
	v_add_f32_e64 v68, v70, -v156
	v_add_f32_e64 v69, v71, -v156
	v_cvt_pk_bf16_f32 v70, v94, v95
	v_exp_f32_e32 v168, v68
	v_exp_f32_e32 v169, v69
	v_cvt_pk_bf16_f32 v68, v88, v89
	v_cvt_pk_bf16_f32 v69, v92, v93
	v_lshl_add_u64 v[150:151], v[150:151], 0, s[4:5]
	v_mfma_f32_32x32x16_bf16 v[32:47], v[172:175], v[84:87], v[32:47]
	v_cvt_pk_bf16_f32 v71, v168, v169
	v_lshl_add_u64 v[152:153], v[152:153], 0, s[4:5]
	v_lshl_add_u64 v[154:155], v[154:155], 0, s[8:9]
	s_waitcnt lgkmcnt(2)
	v_mfma_f32_32x32x16_bf16 v[16:31], v[180:183], v[84:87], v[16:31]
	s_waitcnt lgkmcnt(0)
	v_mfma_f32_32x32x16_bf16 v[48:63], v[64:67], v[68:71], v[48:63]
	v_add_f32_e64 v64, v186, v90
	v_add_f32_e64 v65, v187, v91
	v_add_f32_e64 v64, v92, v64
	v_add_f32_e64 v65, v93, v65
	v_add_f32_e64 v64, v188, v64
	v_add_f32_e64 v65, v189, v65
	v_add_f32_e32 v64, v94, v64
	v_add_f32_e32 v65, v95, v65
	v_mfma_f32_32x32x16_bf16 v[0:15], v[80:83], v[84:87], v[0:15]
	ds_read_b128 v[80:83], v167 offset:13888
	ds_read_b128 v[84:87], v167 offset:9312
	v_add_f32_e64 v92, v190, v64
	v_add_f32_e64 v93, v191, v65
	ds_read_b128 v[64:67], v167 offset:18496
	ds_read_b128 v[88:91], v167 offset:13920
	s_waitcnt lgkmcnt(3)
	v_mfma_f32_32x32x16_bf16 v[32:47], v[80:83], v[68:71], v[32:47]
	v_add_f32_e64 v80, v168, v92
	v_add_f32_e64 v81, v169, v93
	v_add_f32_e64 v168, v192, v80
	v_add_f32_e64 v169, v193, v81
	ds_read_b128 v[80:83], v167 offset:23104
	ds_read_b128 v[92:95], v167 offset:18528
	s_waitcnt lgkmcnt(3)
	v_mfma_f32_32x32x16_bf16 v[16:31], v[64:67], v[68:71], v[16:31]
	v_add_f32_e64 v64, v74, -v156
	v_add_f32_e64 v65, v75, -v156
	v_exp_f32_e32 v74, v64
	v_exp_f32_e32 v75, v65
	v_sub_f32_e32 v64, v76, v156
	v_sub_f32_e32 v65, v77, v156
	s_nop 0
	v_exp_f32_e32 v76, v64
	v_exp_f32_e32 v77, v65
	ds_read_b128 v[64:67], v167 offset:23136
	s_waitcnt lgkmcnt(2)
	v_mfma_f32_32x32x16_bf16 v[0:15], v[80:83], v[68:71], v[0:15]
	v_add_f32_e64 v68, v78, -v156
	v_add_f32_e64 v69, v79, -v156
	v_cvt_pk_bf16_f32 v70, v76, v77
	v_exp_f32_e32 v78, v68
	v_exp_f32_e32 v79, v69
	v_cvt_pk_bf16_f32 v68, v72, v73
	v_add_f32_e32 v72, v72, v168
	v_add_f32_e32 v73, v73, v169
	v_cvt_pk_bf16_f32 v69, v74, v75
	v_add_f32_e32 v72, v194, v72
	v_add_f32_e32 v73, v195, v73
	v_cvt_pk_bf16_f32 v71, v78, v79
	v_add_f32_e32 v72, v74, v72
	v_add_f32_e32 v73, v75, v73
	s_nop 0
	v_add_f32_e32 v72, v196, v72
	v_add_f32_e32 v73, v197, v73
	v_mfma_f32_32x32x16_bf16 v[48:63], v[84:87], v[68:71], v[48:63]
	v_add_f32_e64 v72, v76, v72
	v_add_f32_e64 v73, v77, v73
	v_add_f32_e64 v72, v176, v72
	v_add_f32_e64 v73, v177, v73
	v_add_f32_e64 v72, v78, v72
	v_add_f32_e64 v73, v79, v73
	v_add_f32_e32 v72, v72, v73
	v_mfma_f32_32x32x16_bf16 v[32:47], v[88:91], v[68:71], v[32:47]
	v_add_f32_e32 v166, v166, v72
	v_add_u32_e32 v72, s0, v158
	s_waitcnt vmcnt(2)
	ds_write_b128 v72, v[120:123]
	v_add_u32_e32 v72, s0, v159
	v_add_u32_e32 v73, v72, v160
	v_add_u32_e32 v72, v72, v161
	s_add_i32 s0, s11, s10
	s_waitcnt lgkmcnt(2)
	v_mfma_f32_32x32x16_bf16 v[16:31], v[92:95], v[68:71], v[16:31]
	v_add_u32_e32 v73, 0x2000, v73
	v_add_u32_e32 v72, 0x2000, v72
	s_cmp_eq_u32 s0, 2
	s_waitcnt vmcnt(1)
	ds_write2_b64 v73, v[116:117], v[118:119] offset0:128 offset1:130
	s_waitcnt vmcnt(0)
	ds_write2_b64 v72, v[112:113], v[114:115] offset0:128 offset1:130
	s_waitcnt lgkmcnt(0)
	s_barrier
	v_mfma_f32_32x32x16_bf16 v[0:15], v[64:67], v[68:71], v[0:15]
	s_cbranch_scc1 .LBB0_1285

; DI unsigned pack2(float lo, float hi) { const f32x2 v = (f32x2){lo, hi}; return __builtin_bit_cast(unsigned, __builtin_convertvector(v, bf16x2_t)); }
; #define MFMA32(a, b, c) __builtin_amdgcn_mfma_f32_32x32x16_bf16((a), (b), (c), 0, 0, 0)
; template <int DQK, int MODE>
; DI void attn_phase(const bf16_t* __restrict__ QK, int ldq, const bf16_t* __restrict__ Vt, int VC, bf16_t* __restrict__ O, int ldo, int nhu, bool skip_ctx, const float* __restrict__ qgain, const f32x2* __restrict__ rope, float qscale, char* shm) {
;     ...
;             { const f32x2 m2 = (f32x2){mrun, mrun}; f32x2 ps2 = (f32x2){0.f, 0.f};
; #pragma unroll
;               for (int i = 0; i < 16; i += 2) {
;                   f32x2 a = (f32x2){st0[i], st0[i + 1]} - m2, c = (f32x2){st1[i], st1[i + 1]} - m2;
;                   a[0] = __builtin_amdgcn_exp2f(a[0]); a[1] = __builtin_amdgcn_exp2f(a[1]); c[0] = __builtin_amdgcn_exp2f(c[0]); c[1] = __builtin_amdgcn_exp2f(c[1]);
;                   ps2 += a; ps2 += c; st0[i] = a[0]; st0[i + 1] = a[1]; st1[i] = c[0]; st1[i + 1] = c[1]; }
;               lsum += ps2[0] + ps2[1]; }
; #pragma unroll
;             for (int kb = 0; kb < 2; ++kb)
; #pragma unroll
;                 for (int s = 0; s < 2; ++s) {
;                     u32x4 pw;
;                     if (kb == 0) { pw.x = pack2(st0[8 * s], st0[8 * s + 1]); pw.y = pack2(st0[8 * s + 2], st0[8 * s + 3]); pw.z = pack2(st0[8 * s + 4], st0[8 * s + 5]); pw.w = pack2(st0[8 * s + 6], st0[8 * s + 7]); }
;                     else { pw.x = pack2(st1[8 * s], st1[8 * s + 1]); pw.y = pack2(st1[8 * s + 2], st1[8 * s + 3]); pw.z = pack2(st1[8 * s + 4], st1[8 * s + 5]); pw.w = pack2(st1[8 * s + 6], st1[8 * s + 7]); }
;                     const bf16x8 pb = __builtin_bit_cast(bf16x8, pw);
; #pragma unroll
;                     for (int t = 0; t < 4; ++t) {
;                         const bf16x8 a = *(const bf16x8*)(Vc + (32 * t + r) * VS + (kb * 2 + s) * 32 + h * 16);
;                         oacc[t] = MFMA32(a, pb, oacc[t]);
;                     }
;                 }
.LBB0_3391:
	v_mov_b32_e32 v97, v184
	v_pk_add_f32 v[82:83], v[82:83], v[96:97] neg_lo:[0,1] neg_hi:[0,1]
	v_pk_add_f32 v[80:81], v[80:81], v[96:97] neg_lo:[0,1] neg_hi:[0,1]
	v_exp_f32_e32 v114, v82
	v_exp_f32_e32 v115, v83
	v_pk_add_f32 v[82:83], v[84:85], v[96:97] neg_lo:[0,1] neg_hi:[0,1]
	v_pk_add_f32 v[86:87], v[86:87], v[96:97] neg_lo:[0,1] neg_hi:[0,1]
	v_exp_f32_e32 v116, v82
	v_exp_f32_e32 v117, v83
	ds_read_b128 v[82:85], v196 offset:53248
	ds_read_b128 v[102:105], v196 offset:53280
	v_exp_f32_e32 v80, v80
	v_exp_f32_e32 v81, v81
	v_exp_f32_e32 v118, v86
	v_exp_f32_e32 v119, v87
	v_cvt_pk_bf16_f32 v99, v114, v115
	v_cvt_pk_bf16_f32 v98, v80, v81
	v_cvt_pk_bf16_f32 v100, v116, v117
	v_cvt_pk_bf16_f32 v101, v118, v119
	v_pk_add_f32 v[86:87], v[88:89], v[96:97] neg_lo:[0,1] neg_hi:[0,1]
	v_pk_add_f32 v[64:65], v[64:65], v[96:97] neg_lo:[0,1] neg_hi:[0,1]
	s_waitcnt lgkmcnt(1)
	v_mfma_f32_32x32x16_bf16 v[48:63], v[82:85], v[98:101], v[48:63]
	ds_read_b128 v[82:85], v196 offset:57856
	ds_read_b128 v[106:109], v196 offset:57888
	v_exp_f32_e32 v120, v86
	v_exp_f32_e32 v121, v87
	v_pk_add_f32 v[72:73], v[72:73], v[96:97] neg_lo:[0,1] neg_hi:[0,1]
	v_pk_add_f32 v[76:77], v[76:77], v[96:97] neg_lo:[0,1] neg_hi:[0,1]
	v_add_f32_e32 v80, 0, v80
	v_add_f32_e32 v81, 0, v81
	s_add_i32 s14, s14, s26
	s_waitcnt lgkmcnt(1)
	v_mfma_f32_32x32x16_bf16 v[32:47], v[82:85], v[98:101], v[32:47]
	ds_read_b128 v[82:85], v196 offset:62464
	ds_read_b128 v[86:89], v200 offset:53248
	ds_read_b128 v[110:113], v196 offset:62496
	s_cmpk_gt_i32 s14, 0x1ff
	s_waitcnt lgkmcnt(2)
	v_mfma_f32_32x32x16_bf16 v[16:31], v[82:85], v[98:101], v[16:31]
	v_add_f32_e64 v82, v90, -v96
	v_add_f32_e64 v83, v91, -v97
	v_add_f32_e64 v90, v78, -v96
	v_add_f32_e64 v91, v79, -v97
	v_exp_f32_e32 v122, v82
	v_exp_f32_e32 v123, v83
	v_pk_add_f32 v[82:83], v[92:93], v[96:97] neg_lo:[0,1] neg_hi:[0,1]
	s_nop 0
	v_exp_f32_e32 v124, v82
	s_waitcnt lgkmcnt(1)
	v_mfma_f32_32x32x16_bf16 v[0:15], v[86:89], v[98:101], v[0:15]
	v_add_f32_e64 v86, v94, -v96
	v_add_f32_e64 v87, v95, -v97
	v_exp_f32_e32 v125, v83
	v_exp_f32_e32 v94, v86
	v_exp_f32_e32 v95, v87
	ds_read_b128 v[82:85], v200 offset:53280
	v_exp_f32_e32 v98, v64
	v_exp_f32_e32 v99, v65
	v_pk_add_f32 v[64:65], v[66:67], v[96:97] neg_lo:[0,1] neg_hi:[0,1]
	v_cvt_pk_bf16_f32 v86, v120, v121
	v_cvt_pk_bf16_f32 v87, v122, v123
	v_cvt_pk_bf16_f32 v88, v124, v125
	v_cvt_pk_bf16_f32 v89, v94, v95
	v_exp_f32_e32 v100, v64
	v_exp_f32_e32 v101, v65
	v_pk_add_f32 v[64:65], v[68:69], v[96:97] neg_lo:[0,1] neg_hi:[0,1]
	v_mfma_f32_32x32x16_bf16 v[48:63], v[102:105], v[86:89], v[48:63]
	v_exp_f32_e32 v102, v64
	v_exp_f32_e32 v103, v65
	v_pk_add_f32 v[64:65], v[70:71], v[96:97] neg_lo:[0,1] neg_hi:[0,1]
	v_cvt_pk_bf16_f32 v68, v98, v99
	v_exp_f32_e32 v104, v64
	v_exp_f32_e32 v105, v65
	ds_read_b128 v[64:67], v196 offset:53312
	v_mfma_f32_32x32x16_bf16 v[32:47], v[106:109], v[86:89], v[32:47]
	v_cvt_pk_bf16_f32 v69, v100, v101
	v_cvt_pk_bf16_f32 v70, v102, v103
	v_cvt_pk_bf16_f32 v71, v104, v105
	v_exp_f32_e32 v106, v72
	v_exp_f32_e32 v107, v73
	s_waitcnt lgkmcnt(2)
	v_mfma_f32_32x32x16_bf16 v[16:31], v[110:113], v[86:89], v[16:31]
	v_exp_f32_e32 v110, v76
	v_exp_f32_e32 v111, v77
	s_waitcnt lgkmcnt(1)
	v_mfma_f32_32x32x16_bf16 v[0:15], v[82:85], v[86:89], v[0:15]
	ds_read_b128 v[82:85], v196 offset:57920
	ds_read_b128 v[86:89], v196 offset:53344
	s_waitcnt lgkmcnt(2)
	v_mfma_f32_32x32x16_bf16 v[48:63], v[64:67], v[68:71], v[48:63]
	v_add_f32_e64 v64, v74, -v96
	v_add_f32_e64 v65, v75, -v97
	v_exp_f32_e32 v96, v90
	v_exp_f32_e32 v108, v64
	v_exp_f32_e32 v109, v65
	ds_read_b128 v[64:67], v196 offset:62528
	ds_read_b128 v[72:75], v196 offset:57952
	v_exp_f32_e32 v97, v91
	s_waitcnt lgkmcnt(3)
	v_mfma_f32_32x32x16_bf16 v[32:47], v[82:85], v[68:71], v[32:47]
	ds_read_b128 v[76:79], v200 offset:53312
	ds_read_b128 v[82:85], v196 offset:62560
	ds_read_b128 v[90:93], v200 offset:53344
	s_waitcnt lgkmcnt(0)
	s_barrier
; DI unsigned pack2(float lo, float hi) { const f32x2 v = (f32x2){lo, hi}; return __builtin_bit_cast(unsigned, __builtin_convertvector(v, bf16x2_t)); }
; template <int DQK, int MODE>
; DI void attn_phase(const bf16_t* __restrict__ QK, int ldq, const bf16_t* __restrict__ Vt, int VC, bf16_t* __restrict__ O, int ldo, int nhu, bool skip_ctx, const float* __restrict__ qgain, const f32x2* __restrict__ rope, float qscale, char* shm) {
;     ...
;               lsum += ps2[0] + ps2[1]; }
; #pragma unroll
;             for (int kb = 0; kb < 2; ++kb)
; #pragma unroll
;                 for (int s = 0; s < 2; ++s) {
;                     u32x4 pw;
;                     if (kb == 0) { pw.x = pack2(st0[8 * s], st0[8 * s + 1]); pw.y = pack2(st0[8 * s + 2], st0[8 * s + 3]); pw.z = pack2(st0[8 * s + 4], st0[8 * s + 5]); pw.w = pack2(st0[8 * s + 6], st0[8 * s + 7]); }
;                     else { pw.x = pack2(st1[8 * s], st1[8 * s + 1]); pw.y = pack2(st1[8 * s + 2], st1[8 * s + 3]); pw.z = pack2(st1[8 * s + 4], st1[8 * s + 5]); pw.w = pack2(st1[8 * s + 6], st1[8 * s + 7]); }
;                     const bf16x8 pb = __builtin_bit_cast(bf16x8, pw);
; #pragma unroll
;                     for (int t = 0; t < 4; ++t) {
;                         const bf16x8 a = *(const bf16x8*)(Vc + (32 * t + r) * VS + (kb * 2 + s) * 32 + h * 16);
;                         oacc[t] = MFMA32(a, pb, oacc[t]);
;                     }
;                 }
;             if (kt + 1 < nkt) ATT_STORE((kt + 1) & 1);
;             __syncthreads();
;         }
;     ...
;         const float l = half_swap_sum(lsum), inv = 1.f / l;
;         bf16_t* op = O + qrow * ldo + ooff;
; #pragma unroll
;         for (int t = 0; t < 4; ++t)
; #pragma unroll
;             for (int g = 0; g < 4; g += 2) {
;                 const unsigned ax = pack2(oacc[t][4 * g] * inv, oacc[t][4 * g + 1] * inv), ay = pack2(oacc[t][4 * g + 2] * inv, oacc[t][4 * g + 3] * inv);
;                 const unsigned bx_ = pack2(oacc[t][4 * g + 4] * inv, oacc[t][4 * g + 5] * inv), by_ = pack2(oacc[t][4 * g + 6] * inv, oacc[t][4 * g + 7] * inv);
;                 const auto sx = __builtin_amdgcn_permlane32_swap(ax, bx_, false, false); const auto sy = __builtin_amdgcn_permlane32_swap(ay, by_, false, false);
;                 *(u32x4*)(op + 32 * t + 8 * (g + h)) = (u32x4){sx[0], sy[0], sx[1], sy[1]}; }
	v_mfma_f32_32x32x16_bf16 v[16:31], v[64:67], v[68:71], v[16:31]
	v_cvt_pk_bf16_f32 v64, v106, v107
	v_cvt_pk_bf16_f32 v65, v108, v109
	v_cvt_pk_bf16_f32 v66, v110, v111
	v_cvt_pk_bf16_f32 v67, v96, v97
	v_mfma_f32_32x32x16_bf16 v[0:15], v[76:79], v[68:71], v[0:15]
	v_add_f32_e64 v68, v98, v80
	v_add_f32_e64 v69, v99, v81
	v_add_f32_e64 v68, v114, v68
	v_add_f32_e64 v69, v115, v69
	v_add_f32_e64 v68, v100, v68
	v_add_f32_e64 v69, v101, v69
	v_add_f32_e32 v68, v116, v68
	v_add_f32_e32 v69, v117, v69
	v_mfma_f32_32x32x16_bf16 v[48:63], v[86:89], v[64:67], v[48:63]
	v_add_f32_e64 v68, v102, v68
	v_add_f32_e64 v69, v103, v69
	v_add_f32_e64 v68, v118, v68
	v_add_f32_e64 v69, v119, v69
	v_add_f32_e64 v68, v104, v68
	v_add_f32_e64 v69, v105, v69
	v_add_f32_e32 v68, v120, v68
	v_add_f32_e32 v69, v121, v69
	v_mfma_f32_32x32x16_bf16 v[32:47], v[72:75], v[64:67], v[32:47]
	v_add_f32_e64 v68, v106, v68
	v_add_f32_e64 v69, v107, v69
	v_add_f32_e64 v68, v122, v68
	v_add_f32_e64 v69, v123, v69
	v_add_f32_e64 v68, v108, v68
	v_add_f32_e64 v69, v109, v69
	v_add_f32_e32 v68, v124, v68
	v_add_f32_e32 v69, v125, v69
	v_mfma_f32_32x32x16_bf16 v[16:31], v[82:85], v[64:67], v[16:31]
	v_add_f32_e64 v68, v110, v68
	v_add_f32_e64 v69, v111, v69
	v_add_f32_e64 v68, v94, v68
	v_add_f32_e64 v69, v95, v69
	v_add_f32_e64 v68, v96, v68
	v_add_f32_e64 v69, v97, v69
	v_add_f32_e32 v68, v68, v69
	v_add_f32_e32 v68, v204, v68
	v_mov_b32_e32 v69, v68
	s_nop 1
	v_permlane32_swap_b32_e32 v68, v69
	v_add_f32_e32 v68, v68, v69
	v_div_scale_f32 v69, s[8:9], v68, v68, 1.0
	v_rcp_f32_e32 v70, v69
	v_mfma_f32_32x32x16_bf16 v[0:15], v[90:93], v[64:67], v[0:15]
	v_div_scale_f32 v64, vcc, 1.0, v68, 1.0
	v_fma_f32 v71, -v69, v70, 1.0
	v_fmac_f32_e32 v70, v71, v70
	v_mul_f32_e32 v65, v64, v70
	v_fma_f32 v66, -v69, v65, v64
	v_fmac_f32_e32 v65, v66, v70
	v_fma_f32 v64, -v69, v65, v64
	v_div_fmas_f32 v64, v64, v70, v65
	v_div_fixup_f32 v64, v64, v68, 1.0
	v_lshlrev_b64 v[66:67], 11, v[174:175]
	v_pk_mul_f32 v[48:49], v[48:49], v[64:65] op_sel_hi:[1,0]
	v_pk_mul_f32 v[50:51], v[50:51], v[64:65] op_sel_hi:[1,0]
	v_pk_mul_f32 v[32:33], v[32:33], v[64:65] op_sel_hi:[1,0]
	v_pk_mul_f32 v[34:35], v[34:35], v[64:65] op_sel_hi:[1,0]
	v_pk_mul_f32 v[16:17], v[16:17], v[64:65] op_sel_hi:[1,0]
	v_pk_mul_f32 v[18:19], v[18:19], v[64:65] op_sel_hi:[1,0]
	v_pk_mul_f32 v[0:1], v[0:1], v[64:65] op_sel_hi:[1,0]
	v_pk_mul_f32 v[2:3], v[2:3], v[64:65] op_sel_hi:[1,0]
	v_lshl_add_u64 v[66:67], s[16:17], 0, v[66:67]
	v_cvt_pk_bf16_f32 v48, v48, v49
	v_cvt_pk_bf16_f32 v49, v50, v51
	v_pk_mul_f32 v[50:51], v[52:53], v[64:65] op_sel_hi:[1,0]
	v_pk_mul_f32 v[52:53], v[54:55], v[64:65] op_sel_hi:[1,0]
	v_cvt_pk_bf16_f32 v32, v32, v33
	v_cvt_pk_bf16_f32 v33, v34, v35
	v_pk_mul_f32 v[34:35], v[36:37], v[64:65] op_sel_hi:[1,0]
	v_pk_mul_f32 v[36:37], v[38:39], v[64:65] op_sel_hi:[1,0]
	v_cvt_pk_bf16_f32 v16, v16, v17
	v_cvt_pk_bf16_f32 v17, v18, v19
	v_pk_mul_f32 v[18:19], v[20:21], v[64:65] op_sel_hi:[1,0]
	v_pk_mul_f32 v[20:21], v[22:23], v[64:65] op_sel_hi:[1,0]
	v_cvt_pk_bf16_f32 v0, v0, v1
	v_cvt_pk_bf16_f32 v1, v2, v3
	v_pk_mul_f32 v[2:3], v[4:5], v[64:65] op_sel_hi:[1,0]
	v_pk_mul_f32 v[4:5], v[6:7], v[64:65] op_sel_hi:[1,0]
	v_lshl_add_u64 v[66:67], s[6:7], 1, v[66:67]
	v_cvt_pk_bf16_f32 v50, v50, v51
	v_cvt_pk_bf16_f32 v51, v52, v53
	v_cvt_pk_bf16_f32 v34, v34, v35
	v_cvt_pk_bf16_f32 v35, v36, v37
	v_cvt_pk_bf16_f32 v18, v18, v19
	v_cvt_pk_bf16_f32 v19, v20, v21
	v_cvt_pk_bf16_f32 v2, v2, v3
	v_cvt_pk_bf16_f32 v3, v4, v5
	v_permlane32_swap_b32_e32 v48, v50
	v_permlane32_swap_b32_e32 v49, v51
	v_lshl_add_u64 v[52:53], v[66:67], 0, v[148:149]
	v_permlane32_swap_b32_e32 v32, v34
	v_permlane32_swap_b32_e32 v33, v35
	v_permlane32_swap_b32_e32 v16, v18
	v_permlane32_swap_b32_e32 v17, v19
	v_permlane32_swap_b32_e32 v0, v2
	v_permlane32_swap_b32_e32 v1, v3
	global_store_dwordx4 v[52:53], v[48:51], off
	global_store_dwordx4 v[52:53], v[32:35], off offset:64
	global_store_dwordx4 v[52:53], v[16:19], off offset:128
	v_pk_mul_f32 v[48:49], v[56:57], v[64:65] op_sel_hi:[1,0]
	v_pk_mul_f32 v[50:51], v[58:59], v[64:65] op_sel_hi:[1,0]
	v_pk_mul_f32 v[32:33], v[40:41], v[64:65] op_sel_hi:[1,0]
	v_pk_mul_f32 v[34:35], v[42:43], v[64:65] op_sel_hi:[1,0]
	v_pk_mul_f32 v[16:17], v[24:25], v[64:65] op_sel_hi:[1,0]
	v_pk_mul_f32 v[18:19], v[26:27], v[64:65] op_sel_hi:[1,0]
	global_store_dwordx4 v[52:53], v[0:3], off offset:192
	v_cvt_pk_bf16_f32 v48, v48, v49
	v_cvt_pk_bf16_f32 v49, v50, v51
	v_pk_mul_f32 v[0:1], v[8:9], v[64:65] op_sel_hi:[1,0]
	v_pk_mul_f32 v[2:3], v[10:11], v[64:65] op_sel_hi:[1,0]
	v_pk_mul_f32 v[50:51], v[60:61], v[64:65] op_sel_hi:[1,0]
	v_pk_mul_f32 v[54:55], v[62:63], v[64:65] op_sel_hi:[1,0]
	v_cvt_pk_bf16_f32 v32, v32, v33
	v_cvt_pk_bf16_f32 v33, v34, v35
	v_pk_mul_f32 v[34:35], v[44:45], v[64:65] op_sel_hi:[1,0]
	v_pk_mul_f32 v[36:37], v[46:47], v[64:65] op_sel_hi:[1,0]
	v_cvt_pk_bf16_f32 v16, v16, v17
	v_cvt_pk_bf16_f32 v17, v18, v19
	v_pk_mul_f32 v[18:19], v[28:29], v[64:65] op_sel_hi:[1,0]
	v_pk_mul_f32 v[20:21], v[30:31], v[64:65] op_sel_hi:[1,0]
	v_cvt_pk_bf16_f32 v0, v0, v1
	v_cvt_pk_bf16_f32 v1, v2, v3
	v_pk_mul_f32 v[2:3], v[12:13], v[64:65] op_sel_hi:[1,0]
	v_pk_mul_f32 v[4:5], v[14:15], v[64:65] op_sel_hi:[1,0]
	v_cvt_pk_bf16_f32 v50, v50, v51
	v_cvt_pk_bf16_f32 v51, v54, v55
	v_cvt_pk_bf16_f32 v34, v34, v35
	v_cvt_pk_bf16_f32 v35, v36, v37
	v_cvt_pk_bf16_f32 v18, v18, v19
	v_cvt_pk_bf16_f32 v19, v20, v21
	v_cvt_pk_bf16_f32 v2, v2, v3
	v_cvt_pk_bf16_f32 v3, v4, v5
	v_permlane32_swap_b32_e32 v48, v50
	v_permlane32_swap_b32_e32 v49, v51
	v_permlane32_swap_b32_e32 v32, v34
	v_permlane32_swap_b32_e32 v33, v35
	v_permlane32_swap_b32_e32 v16, v18
	v_permlane32_swap_b32_e32 v17, v19
	v_permlane32_swap_b32_e32 v0, v2
	v_permlane32_swap_b32_e32 v1, v3
	global_store_dwordx4 v[52:53], v[48:51], off offset:32
	global_store_dwordx4 v[52:53], v[32:35], off offset:96
	global_store_dwordx4 v[52:53], v[16:19], off offset:160
	global_store_dwordx4 v[52:53], v[0:3], off offset:224
	s_cbranch_scc1 .LBB0_3397

; DI unsigned pack2(float lo, float hi) { const f32x2 v = (f32x2){lo, hi}; return __builtin_bit_cast(unsigned, __builtin_convertvector(v, bf16x2_t)); }
; #define MFMA32(a, b, c) __builtin_amdgcn_mfma_f32_32x32x16_bf16((a), (b), (c), 0, 0, 0)
; template <int DQK, int MODE>
; DI void attn_phase(const bf16_t* __restrict__ QK, int ldq, const bf16_t* __restrict__ Vt, int VC, bf16_t* __restrict__ O, int ldo, int nhu, bool skip_ctx, const float* __restrict__ qgain, const f32x2* __restrict__ rope, float qscale, char* shm) {
;     ...
;             { const f32x2 m2 = (f32x2){mrun, mrun}; f32x2 ps2 = (f32x2){0.f, 0.f};
; #pragma unroll
;               for (int i = 0; i < 16; i += 2) {
;                   f32x2 a = (f32x2){st0[i], st0[i + 1]} - m2, c = (f32x2){st1[i], st1[i + 1]} - m2;
;                   a[0] = __builtin_amdgcn_exp2f(a[0]); a[1] = __builtin_amdgcn_exp2f(a[1]); c[0] = __builtin_amdgcn_exp2f(c[0]); c[1] = __builtin_amdgcn_exp2f(c[1]);
;                   ps2 += a; ps2 += c; st0[i] = a[0]; st0[i + 1] = a[1]; st1[i] = c[0]; st1[i + 1] = c[1]; }
;               lsum += ps2[0] + ps2[1]; }
; #pragma unroll
;             for (int kb = 0; kb < 2; ++kb)
; #pragma unroll
;                 for (int s = 0; s < 2; ++s) {
;                     u32x4 pw;
;                     if (kb == 0) { pw.x = pack2(st0[8 * s], st0[8 * s + 1]); pw.y = pack2(st0[8 * s + 2], st0[8 * s + 3]); pw.z = pack2(st0[8 * s + 4], st0[8 * s + 5]); pw.w = pack2(st0[8 * s + 6], st0[8 * s + 7]); }
;                     else { pw.x = pack2(st1[8 * s], st1[8 * s + 1]); pw.y = pack2(st1[8 * s + 2], st1[8 * s + 3]); pw.z = pack2(st1[8 * s + 4], st1[8 * s + 5]); pw.w = pack2(st1[8 * s + 6], st1[8 * s + 7]); }
;                     const bf16x8 pb = __builtin_bit_cast(bf16x8, pw);
; #pragma unroll
;                     for (int t = 0; t < 4; ++t) {
;                         const bf16x8 a = *(const bf16x8*)(Vc + (32 * t + r) * VS + (kb * 2 + s) * 32 + h * 16);
;                         oacc[t] = MFMA32(a, pb, oacc[t]);
;                     }
;                 }
;             if (kt + 1 < nkt) ATT_STORE((kt + 1) & 1);
;             __syncthreads();
.LBB0_3393:
	v_sub_f32_e32 v80, v80, v184
	v_sub_f32_e32 v81, v81, v184
	s_cmp_eq_u32 s8, 1
	v_exp_f32_e32 v222, v80
	v_exp_f32_e32 v223, v81
	v_sub_f32_e32 v80, v82, v184
	v_sub_f32_e32 v81, v83, v184
	s_cselect_b32 s8, 0x8c00, 0
	v_exp_f32_e32 v224, v80
	v_exp_f32_e32 v225, v81
	v_sub_f32_e32 v80, v84, v184
	v_sub_f32_e32 v81, v85, v184
	v_add_u32_e32 v185, s9, v196
	v_exp_f32_e32 v226, v80
	v_exp_f32_e32 v227, v81
	ds_read_b128 v[80:83], v185 offset:17408
	ds_read_b128 v[206:209], v185 offset:17440
	v_sub_f32_e32 v84, v86, v184
	v_sub_f32_e32 v85, v87, v184
	v_cvt_pk_bf16_f32 v86, v226, v227
	v_exp_f32_e32 v228, v84
	v_exp_f32_e32 v229, v85
	v_cvt_pk_bf16_f32 v84, v222, v223
	v_cvt_pk_bf16_f32 v85, v224, v225
	v_sub_f32_e32 v88, v88, v184
	v_sub_f32_e32 v89, v89, v184
	v_cvt_pk_bf16_f32 v87, v228, v229
	v_sub_f32_e32 v64, v64, v184
	v_sub_f32_e32 v65, v65, v184
	v_exp_f32_e32 v230, v88
	s_waitcnt lgkmcnt(1)
	v_mfma_f32_32x32x16_bf16 v[48:63], v[80:83], v[84:87], v[48:63]
	ds_read_b128 v[80:83], v185 offset:22016
	ds_read_b128 v[210:213], v185 offset:22048
	v_exp_f32_e32 v231, v89
	v_exp_f32_e32 v88, v64
	v_exp_f32_e32 v89, v65
	v_add_f32_e32 v64, 0, v222
	v_add_f32_e32 v65, 0, v223
	v_sub_f32_e32 v72, v72, v184
	v_sub_f32_e32 v73, v73, v184
	s_add_i32 s9, s8, 0
	s_waitcnt lgkmcnt(1)
	v_mfma_f32_32x32x16_bf16 v[32:47], v[80:83], v[84:87], v[32:47]
	ds_read_b128 v[80:83], v185 offset:26624
	ds_read_b128 v[214:217], v185 offset:31232
	ds_read_b128 v[218:221], v185 offset:26656
	v_exp_f32_e32 v72, v72
	v_exp_f32_e32 v73, v73
	s_add_i32 s0, s0, 1
	v_lshl_add_u64 v[176:177], v[176:177], 0, s[2:3]
	v_lshl_add_u64 v[178:179], v[178:179], 0, s[2:3]
	s_waitcnt lgkmcnt(2)
	v_mfma_f32_32x32x16_bf16 v[16:31], v[80:83], v[84:87], v[16:31]
	v_add_f32_e64 v80, v90, -v184
	v_add_f32_e64 v81, v91, -v184
	v_add_f32_e64 v90, v88, v64
	v_add_f32_e64 v91, v89, v65
	v_exp_f32_e32 v232, v80
	v_exp_f32_e32 v233, v81
	v_sub_f32_e32 v80, v92, v184
	v_sub_f32_e32 v81, v93, v184
	v_sub_f32_e32 v64, v66, v184
	v_sub_f32_e32 v65, v67, v184
	v_exp_f32_e32 v234, v80
	s_waitcnt lgkmcnt(1)
	v_mfma_f32_32x32x16_bf16 v[0:15], v[214:217], v[84:87], v[0:15]
	v_add_f32_e64 v84, v94, -v184
	v_add_f32_e64 v85, v95, -v184
	v_exp_f32_e32 v235, v81
	v_exp_f32_e32 v214, v84
	v_exp_f32_e32 v215, v85
	v_exp_f32_e32 v92, v64
	v_exp_f32_e32 v93, v65
	v_sub_f32_e32 v64, v68, v184
	v_sub_f32_e32 v65, v69, v184
	ds_read_b128 v[80:83], v185 offset:31264
	v_cvt_pk_bf16_f32 v84, v230, v231
	v_cvt_pk_bf16_f32 v85, v232, v233
	v_cvt_pk_bf16_f32 v86, v234, v235
	v_cvt_pk_bf16_f32 v87, v214, v215
	v_exp_f32_e32 v94, v64
	v_exp_f32_e32 v95, v65
	ds_read_b128 v[64:67], v185 offset:17472
	v_mfma_f32_32x32x16_bf16 v[48:63], v[206:209], v[84:87], v[48:63]
	v_add_f32_e64 v68, v70, -v184
	v_add_f32_e64 v69, v71, -v184
	v_cvt_pk_bf16_f32 v70, v94, v95
	v_exp_f32_e32 v206, v68
	v_exp_f32_e32 v207, v69
	v_cvt_pk_bf16_f32 v68, v88, v89
	v_cvt_pk_bf16_f32 v69, v92, v93
	v_lshl_add_u64 v[180:181], v[180:181], 0, s[4:5]
	v_mfma_f32_32x32x16_bf16 v[32:47], v[210:213], v[84:87], v[32:47]
	v_cvt_pk_bf16_f32 v71, v206, v207
	s_cmp_eq_u32 s0, 36
	v_lshl_add_u64 v[182:183], v[182:183], 0, s[4:5]
	s_waitcnt lgkmcnt(2)
	v_mfma_f32_32x32x16_bf16 v[16:31], v[218:221], v[84:87], v[16:31]
	s_waitcnt lgkmcnt(0)
	v_mfma_f32_32x32x16_bf16 v[48:63], v[64:67], v[68:71], v[48:63]
	v_add_f32_e64 v64, v224, v90
	v_add_f32_e64 v65, v225, v91
	v_add_f32_e64 v64, v92, v64
	v_add_f32_e64 v65, v93, v65
	v_add_f32_e64 v64, v226, v64
	v_add_f32_e64 v65, v227, v65
	v_add_f32_e32 v64, v94, v64
	v_add_f32_e32 v65, v95, v65
	v_mfma_f32_32x32x16_bf16 v[0:15], v[80:83], v[84:87], v[0:15]
	ds_read_b128 v[80:83], v185 offset:22080
	ds_read_b128 v[84:87], v185 offset:17504
	v_add_f32_e64 v92, v228, v64
	v_add_f32_e64 v93, v229, v65
	ds_read_b128 v[64:67], v185 offset:26688
	ds_read_b128 v[88:91], v185 offset:22112
	s_waitcnt lgkmcnt(3)
	v_mfma_f32_32x32x16_bf16 v[32:47], v[80:83], v[68:71], v[32:47]
	v_add_f32_e64 v80, v206, v92
	v_add_f32_e64 v81, v207, v93
	v_add_f32_e64 v206, v230, v80
	v_add_f32_e64 v207, v231, v81
	ds_read_b128 v[80:83], v185 offset:31296
	ds_read_b128 v[92:95], v185 offset:26720
	s_waitcnt lgkmcnt(3)
	v_mfma_f32_32x32x16_bf16 v[16:31], v[64:67], v[68:71], v[16:31]
	v_add_f32_e64 v64, v74, -v184
	v_add_f32_e64 v65, v75, -v184
	v_exp_f32_e32 v74, v64
	v_exp_f32_e32 v75, v65
	v_sub_f32_e32 v64, v76, v184
	v_sub_f32_e32 v65, v77, v184
	s_nop 0
	v_exp_f32_e32 v76, v64
	v_exp_f32_e32 v77, v65
	ds_read_b128 v[64:67], v185 offset:31328
	s_waitcnt lgkmcnt(2)
	v_mfma_f32_32x32x16_bf16 v[0:15], v[80:83], v[68:71], v[0:15]
	v_add_f32_e64 v68, v78, -v184
	v_add_f32_e64 v69, v79, -v184
	v_cvt_pk_bf16_f32 v70, v76, v77
	v_exp_f32_e32 v78, v68
	v_exp_f32_e32 v79, v69
	v_cvt_pk_bf16_f32 v68, v72, v73
	v_add_f32_e32 v72, v72, v206
	v_add_f32_e32 v73, v73, v207
	v_cvt_pk_bf16_f32 v69, v74, v75
	v_add_f32_e32 v72, v232, v72
	v_add_f32_e32 v73, v233, v73
	v_cvt_pk_bf16_f32 v71, v78, v79
	v_add_f32_e32 v72, v74, v72
	v_add_f32_e32 v73, v75, v73
	s_nop 0
	v_add_f32_e32 v72, v234, v72
	v_add_f32_e32 v73, v235, v73
	v_mfma_f32_32x32x16_bf16 v[48:63], v[84:87], v[68:71], v[48:63]
	v_add_f32_e64 v72, v76, v72
	v_add_f32_e64 v73, v77, v73
	v_add_f32_e64 v72, v214, v72
	v_add_f32_e64 v73, v215, v73
	v_add_f32_e64 v72, v78, v72
	v_add_f32_e64 v73, v79, v73
	v_add_f32_e32 v72, v72, v73
	v_mfma_f32_32x32x16_bf16 v[32:47], v[88:91], v[68:71], v[32:47]
	v_add_f32_e32 v204, v204, v72
	v_add3_u32 v72, s9, v189, v190
	s_waitcnt vmcnt(3)
	ds_write_b128 v72, v[140:143]
	v_add3_u32 v72, s9, v191, v192
	s_waitcnt vmcnt(2)
	ds_write_b128 v72, v[136:139]
	v_add_u32_e32 v72, s8, v188
	v_add_u32_e32 v73, v72, v193
	s_waitcnt lgkmcnt(3)
	v_mfma_f32_32x32x16_bf16 v[16:31], v[92:95], v[68:71], v[16:31]
	v_add_u32_e32 v72, v72, v194
	v_add_u32_e32 v73, 0x4000, v73
	s_waitcnt vmcnt(1)
	ds_write2_b64 v73, v[132:133], v[134:135] offset0:128 offset1:130
	s_waitcnt lgkmcnt(3)
	v_mfma_f32_32x32x16_bf16 v[0:15], v[64:67], v[68:71], v[0:15]
	v_add_u32_e32 v64, 0x4000, v72
	s_waitcnt vmcnt(0)
	ds_write2_b64 v64, v[128:129], v[130:131] offset0:128 offset1:130
	s_waitcnt lgkmcnt(0)
	s_barrier
	s_cbranch_scc1 .LBB0_3389
